# attention: stage-write of the next K/V tile issued before the PV MFMAs (computing waves) instead of at the end of the step; stacked on the GEMM loop edits
# baseline (speedup 1.0000x reference)
.LBB0_963:
	v_sub_f32_e32 v15, v80, v214
	v_sub_f32_e32 v80, v97, v214
	v_exp_f32_e32 v216, v80
	v_sub_f32_e32 v80, v81, v214
	v_exp_f32_e32 v217, v80
	v_sub_f32_e32 v80, v98, v214
	v_exp_f32_e32 v218, v80
	v_sub_f32_e32 v80, v82, v214
	v_exp_f32_e32 v219, v80
	v_sub_f32_e32 v80, v99, v214
	v_exp_f32_e32 v220, v80
	v_sub_f32_e32 v80, v83, v214
	v_exp_f32_e32 v221, v80
	v_sub_f32_e32 v80, v100, v214
	v_exp_f32_e32 v222, v80
	v_sub_f32_e32 v80, v84, v214
	v_exp_f32_e32 v223, v80
	v_sub_f32_e32 v80, v101, v214
	v_exp_f32_e32 v224, v80
	v_sub_f32_e32 v80, v85, v214
	v_exp_f32_e32 v225, v80
	v_sub_f32_e32 v80, v102, v214
	v_exp_f32_e32 v226, v80
	v_sub_f32_e32 v80, v86, v214
	v_exp_f32_e32 v227, v80
	v_sub_f32_e32 v80, v103, v214
	v_exp_f32_e32 v228, v80
	v_sub_f32_e32 v80, v87, v214
	v_exp_f32_e32 v229, v80
	v_sub_f32_e32 v80, v104, v214
	v_exp_f32_e32 v230, v80
	v_sub_f32_e32 v80, v88, v214
	v_exp_f32_e32 v231, v80
	v_sub_f32_e32 v80, v105, v214
	v_exp_f32_e32 v232, v80
	v_sub_f32_e32 v80, v89, v214
	v_exp_f32_e32 v233, v80
	v_sub_f32_e32 v80, v106, v214
	v_exp_f32_e32 v234, v80
	v_sub_f32_e32 v80, v90, v214
	v_exp_f32_e32 v235, v80
	v_sub_f32_e32 v80, v107, v214
	v_exp_f32_e32 v236, v80
	v_sub_f32_e32 v80, v91, v214
	v_exp_f32_e32 v237, v80
	v_sub_f32_e32 v80, v108, v214
	v_exp_f32_e32 v238, v80
	v_sub_f32_e32 v80, v92, v214
	v_exp_f32_e32 v239, v80
	v_sub_f32_e32 v80, v109, v214
	v_exp_f32_e32 v240, v80
	v_sub_f32_e32 v80, v93, v214
	v_exp_f32_e32 v241, v80
	v_sub_f32_e32 v80, v110, v214
	v_exp_f32_e32 v242, v80
	v_sub_f32_e32 v80, v94, v214
	v_exp_f32_e32 v243, v80
	v_sub_f32_e32 v80, v111, v214
	v_sub_f32_e32 v14, v96, v214
	v_exp_f32_e32 v244, v80
	v_sub_f32_e32 v80, v95, v214
	v_exp_f32_e32 v14, v14
	v_exp_f32_e32 v15, v15
	v_exp_f32_e32 v245, v80
	v_cvt_pk_bf16_f32 v96, v14, v216
	v_cvt_pk_bf16_f32 v104, v15, v217
	v_pk_add_f32 v[14:15], v[14:15], 0 op_sel_hi:[1,0]
	v_pk_add_f32 v[216:217], v[216:217], 0 op_sel_hi:[1,0]
	v_pk_add_f32 v[14:15], v[218:219], v[14:15]
	v_pk_add_f32 v[216:217], v[220:221], v[216:217]
	ds_read_b128 v[80:83], v1 offset:30208
	ds_read_b128 v[84:87], v1 offset:30240
	ds_read_b128 v[88:91], v1 offset:30272
	ds_read_b128 v[92:95], v1 offset:30304
	v_pk_add_f32 v[14:15], v[222:223], v[14:15]
	v_pk_add_f32 v[216:217], v[224:225], v[216:217]
	v_pk_add_f32 v[14:15], v[226:227], v[14:15]
	v_pk_add_f32 v[216:217], v[228:229], v[216:217]
	v_pk_add_f32 v[14:15], v[230:231], v[14:15]
	v_pk_add_f32 v[216:217], v[232:233], v[216:217]
	v_pk_add_f32 v[14:15], v[234:235], v[14:15]
	v_pk_add_f32 v[216:217], v[236:237], v[216:217]
	v_pk_add_f32 v[14:15], v[238:239], v[14:15]
	v_pk_add_f32 v[216:217], v[240:241], v[216:217]
	v_pk_add_f32 v[14:15], v[242:243], v[14:15]
	v_pk_add_f32 v[216:217], v[244:245], v[216:217]
	v_cvt_pk_bf16_f32 v97, v218, v220
	v_pk_add_f32 v[14:15], v[14:15], v[216:217]
	v_cvt_pk_bf16_f32 v98, v222, v224
	v_cvt_pk_bf16_f32 v99, v226, v228
	v_cvt_pk_bf16_f32 v100, v230, v232
	v_cvt_pk_bf16_f32 v101, v234, v236
	v_cvt_pk_bf16_f32 v102, v238, v240
	v_cvt_pk_bf16_f32 v103, v242, v244
	v_cvt_pk_bf16_f32 v105, v219, v221
	v_cvt_pk_bf16_f32 v106, v223, v225
	v_cvt_pk_bf16_f32 v107, v227, v229
	v_cvt_pk_bf16_f32 v108, v231, v233
	v_cvt_pk_bf16_f32 v109, v235, v237
	v_cvt_pk_bf16_f32 v110, v239, v241
	v_cvt_pk_bf16_f32 v111, v243, v245
	v_add_f32_e32 v14, v14, v15
	s_andn2_b64 vcc, exec, s[30:31]
	s_cbranch_vccnz .Lattn_nowr
	s_bitcmp1_b32 s34, 0
	s_cselect_b32 s30, 0xac00, 0
	v_add_u32_e32 v216, s30, v207
	s_waitcnt vmcnt(4)
	ds_write_b128 v216, v[112:115]
	s_waitcnt vmcnt(3)
	ds_write_b128 v216, v[116:119] offset:128
	s_waitcnt vmcnt(2)
	ds_write_b128 v216, v[120:123] offset:256
	v_add_u32_e32 v217, s30, v208
	s_waitcnt vmcnt(1)
	ds_write_b128 v217, v[124:127] offset:25600
	s_waitcnt vmcnt(0)
	ds_write_b128 v217, v[128:131] offset:25664
.Lattn_nowr:
	v_mfma_f32_32x32x16_bf16 v[64:79], v[180:183], v[96:99], v[64:79]
	v_mfma_f32_32x32x16_bf16 v[64:79], v[10:13], v[100:103], v[64:79]
	v_mfma_f32_32x32x16_bf16 v[64:79], v[6:9], v[104:107], v[64:79]
	v_mfma_f32_32x32x16_bf16 v[64:79], v[2:5], v[108:111], v[64:79]
	ds_read_b128 v[2:5], v1 offset:34816
	ds_read_b128 v[6:9], v1 offset:34848
	ds_read_b128 v[10:13], v1 offset:34880
	ds_read_b128 v[180:183], v1 offset:34912
	s_waitcnt lgkmcnt(7)
	v_mfma_f32_32x32x16_bf16 v[48:63], v[80:83], v[96:99], v[48:63]
	s_waitcnt lgkmcnt(6)
	v_mfma_f32_32x32x16_bf16 v[48:63], v[84:87], v[100:103], v[48:63]
	s_waitcnt lgkmcnt(5)
	v_mfma_f32_32x32x16_bf16 v[48:63], v[88:91], v[104:107], v[48:63]
	s_waitcnt lgkmcnt(4)
	v_mfma_f32_32x32x16_bf16 v[48:63], v[92:95], v[108:111], v[48:63]
	ds_read_b128 v[80:83], v1 offset:39424
	ds_read_b128 v[84:87], v1 offset:39456
	ds_read_b128 v[88:91], v1 offset:39488
	ds_read_b128 v[92:95], v1 offset:39520
	s_waitcnt lgkmcnt(7)
	v_mfma_f32_32x32x16_bf16 v[32:47], v[2:5], v[96:99], v[32:47]
	s_waitcnt lgkmcnt(6)
	v_mfma_f32_32x32x16_bf16 v[32:47], v[6:9], v[100:103], v[32:47]
	s_waitcnt lgkmcnt(5)
	v_mfma_f32_32x32x16_bf16 v[32:47], v[10:13], v[104:107], v[32:47]
	s_waitcnt lgkmcnt(4)
	v_mfma_f32_32x32x16_bf16 v[32:47], v[180:183], v[108:111], v[32:47]
	s_waitcnt lgkmcnt(3)
	v_mfma_f32_32x32x16_bf16 v[16:31], v[80:83], v[96:99], v[16:31]
	v_add_f32_e32 v213, v213, v14
	s_waitcnt lgkmcnt(2)
	v_mfma_f32_32x32x16_bf16 v[16:31], v[84:87], v[100:103], v[16:31]
	s_waitcnt lgkmcnt(1)
	v_mfma_f32_32x32x16_bf16 v[16:31], v[88:91], v[104:107], v[16:31]
	s_waitcnt lgkmcnt(0)
	v_mfma_f32_32x32x16_bf16 v[16:31], v[92:95], v[108:111], v[16:31]
	s_branch .LBB0_958
